# GQA loop: LDS-DMA issue with s_add_i32 m0 one instruction early (no s_mov/s_nop), permlane wait states filled by it: 4 issue slots less per key tile
# speedup vs baseline: 1.0111x; 1.0043x over previous
.LBB0_707:
	s_add_i32 s22, s23, 2
	v_add_u32_e32 v186, s0, v207
	ds_read_b64_tr_b16 v[178:179], v186 offset:24576
	ds_read_b64_tr_b16 v[180:181], v186 offset:25088
	s_waitcnt lgkmcnt(9)
	v_mfma_f32_32x32x16_bf16 v[98:113], v[174:177], v[142:145], v[34:49]
	v_add_f32_e32 v82, v66, v67
	v_add_f32_e32 v82, v68, v82
	v_add_f32_e32 v82, v69, v82
	v_add_f32_e32 v82, v70, v82
	v_add_f32_e32 v82, v71, v82
	v_cvt_pk_bf16_f32 v134, v66, v67
	v_cvt_pk_bf16_f32 v135, v68, v69
	ds_read_b64_tr_b16 v[174:175], v186 offset:28672
	ds_read_b64_tr_b16 v[176:177], v186 offset:29184
	v_add_f32_e32 v66, v72, v82
	s_waitcnt lgkmcnt(10)
	v_mfma_f32_32x32x16_bf16 v[82:97], v[170:173], v[142:145], v[34:49]
	v_add_f32_e32 v66, v73, v66
	v_add_f32_e32 v66, v74, v66
	v_add_f32_e32 v114, v75, v66
	v_cvt_pk_bf16_f32 v136, v70, v71
	v_cvt_pk_bf16_f32 v137, v72, v73
	ds_read_b64_tr_b16 v[66:67], v186 offset:25600
	ds_read_b64_tr_b16 v[68:69], v186 offset:26112
	s_waitcnt lgkmcnt(11)
	v_mfma_f32_32x32x16_bf16 v[98:113], v[166:169], v[138:141], v[98:113]
	v_add_f32_e32 v70, v76, v114
	v_add_f32_e32 v70, v77, v70
	v_add_f32_e32 v70, v78, v70
	v_add_f32_e32 v114, v79, v70
	v_cvt_pk_bf16_f32 v126, v74, v75
	v_cvt_pk_bf16_f32 v127, v76, v77
	ds_read_b64_tr_b16 v[70:71], v186 offset:29696
	ds_read_b64_tr_b16 v[72:73], v186 offset:30208
	s_waitcnt lgkmcnt(12)
	v_mfma_f32_32x32x16_bf16 v[82:97], v[162:165], v[138:141], v[82:97]
	v_add_f32_e32 v74, v80, v114
	v_add_f32_e32 v74, v81, v74
	v_add_f32_e32 v74, v50, v74
	v_add_f32_e32 v114, v51, v74
	v_cvt_pk_bf16_f32 v128, v78, v79
	v_cvt_pk_bf16_f32 v129, v80, v81
	ds_read_b64_tr_b16 v[74:75], v186 offset:26624
	ds_read_b64_tr_b16 v[76:77], v186 offset:27136
	s_waitcnt lgkmcnt(13)
	v_mfma_f32_32x32x16_bf16 v[98:113], v[158:161], v[130:133], v[98:113]
	v_add_f32_e32 v78, v52, v114
	v_add_f32_e32 v78, v53, v78
	v_add_f32_e32 v78, v54, v78
	v_add_f32_e32 v78, v55, v78
	v_cvt_pk_bf16_f32 v118, v50, v51
	v_cvt_pk_bf16_f32 v119, v52, v53
	ds_read_b64_tr_b16 v[50:51], v186 offset:30720
	ds_read_b64_tr_b16 v[52:53], v186 offset:31232
	s_waitcnt lgkmcnt(14)
	v_mfma_f32_32x32x16_bf16 v[82:97], v[154:157], v[130:133], v[82:97]
	v_add_f32_e32 v78, v56, v78
	v_add_f32_e32 v78, v57, v78
	v_add_f32_e32 v78, v58, v78
	v_add_f32_e32 v78, v59, v78
	v_cvt_pk_bf16_f32 v120, v54, v55
	v_cvt_pk_bf16_f32 v121, v56, v57
	ds_read_b64_tr_b16 v[54:55], v186 offset:27648
	ds_read_b64_tr_b16 v[56:57], v186 offset:28160
	s_waitcnt lgkmcnt(14)
	v_mfma_f32_32x32x16_bf16 v[98:113], v[150:153], v[122:125], v[98:113]
	v_add_f32_e32 v78, v60, v78
	v_add_f32_e32 v78, v61, v78
	v_add_f32_e32 v78, v62, v78
	v_add_f32_e32 v78, v63, v78
	v_cvt_pk_bf16_f32 v114, v58, v59
	v_cvt_pk_bf16_f32 v115, v60, v61
	ds_read_b64_tr_b16 v[58:59], v186 offset:31744
	ds_read_b64_tr_b16 v[60:61], v186 offset:32256
	v_mfma_f32_32x32x16_bf16 v[82:97], v[146:149], v[122:125], v[82:97]
	v_add_f32_e32 v78, v64, v78
	v_add_f32_e32 v78, v65, v78
	v_cvt_pk_bf16_f32 v116, v62, v63
	v_cvt_pk_bf16_f32 v117, v64, v65
	s_cmpk_gt_u32 s22, 0x7c
	s_cselect_b64 s[0:1], -1, 0
	s_cmpk_lt_u32 s22, 0x7d
	s_cselect_b32 s4, 0, 0xffffff80
	s_cselect_b32 s5, s9, s20
	s_add_i32 s4, s4, s23
	s_lshl_b32 s4, s4, 6
	s_add_i32 s4, s4, s5
	s_addk_i32 s4, 0x140
	s_add_i32 m0, s24, s18
	v_mad_i64_i32 v[62:63], s[4:5], s4, v217, v[192:193]
	global_load_lds_dwordx4 v[62:63], off
	v_max_f32_e32 v62, v98, v99
	v_max3_f32 v63, v100, v101, v83
	v_max3_f32 v62, v62, v82, v84
	v_max3_f32 v62, v62, v85, v102
	v_max3_f32 v63, v63, v104, v105
	v_max3_f32 v62, v62, v103, v86
	v_max3_f32 v63, v63, v88, v89
	v_max3_f32 v62, v62, v87, v106
	v_max3_f32 v63, v63, v108, v109
	v_max3_f32 v62, v62, v107, v90
	v_max3_f32 v63, v63, v92, v93
	v_max3_f32 v62, v62, v91, v110
	v_max3_f32 v63, v63, v112, v113
	v_max3_f32 v62, v62, v111, v94
	v_max3_f32 v63, v63, v96, v97
	v_max3_f32 v62, v62, v95, v63
	v_mov_b32_e32 v63, v62
	s_add_i32 m0, s21, s19
	s_nop 0
	v_permlane32_swap_b32_e32 v62, v63
	global_load_lds_dwordx4 v[196:197], off
	v_max_f32_e32 v62, v62, v63
	v_cmp_lt_f32_e32 vcc, s51, v62
	s_cmp_lg_u64 vcc, 0
	v_add_f32_e32 v224, v224, v78
	s_cselect_b64 s[4:5], -1, 0
	s_cbranch_vccnz .LBB0_715

.LBB0_710:
	s_add_i32 s4, s21, 0x2000
	s_cmpk_lg_i32 s21, 0x4000
	s_cselect_b32 s25, s4, 0
	v_add_u32_e32 v186, s24, v207
	ds_read_b64_tr_b16 v[150:151], v186 offset:24576
	ds_read_b64_tr_b16 v[152:153], v186 offset:25088
	s_waitcnt lgkmcnt(9)
	v_mfma_f32_32x32x16_bf16 v[66:81], v[62:65], v[142:145], v[34:49]
	v_add_f32_e32 v50, v98, v99
	v_add_f32_e32 v50, v100, v50
	v_add_f32_e32 v50, v101, v50
	v_add_f32_e32 v50, v102, v50
	v_add_f32_e32 v50, v103, v50
	v_cvt_pk_bf16_f32 v134, v98, v99
	v_cvt_pk_bf16_f32 v135, v100, v101
	ds_read_b64_tr_b16 v[146:147], v186 offset:28672
	ds_read_b64_tr_b16 v[148:149], v186 offset:29184
	v_add_f32_e32 v50, v104, v50
	v_add_f32_e32 v50, v105, v50
	v_add_f32_e32 v50, v106, v50
	v_add_f32_e32 v114, v107, v50
	s_waitcnt lgkmcnt(10)
	v_mfma_f32_32x32x16_bf16 v[50:65], v[174:177], v[142:145], v[34:49]
	v_cvt_pk_bf16_f32 v136, v102, v103
	v_cvt_pk_bf16_f32 v137, v104, v105
	ds_read_b64_tr_b16 v[98:99], v186 offset:25600
	ds_read_b64_tr_b16 v[100:101], v186 offset:26112
	s_waitcnt lgkmcnt(11)
	v_mfma_f32_32x32x16_bf16 v[66:81], v[178:181], v[138:141], v[66:81]
	v_add_f32_e32 v102, v108, v114
	v_add_f32_e32 v102, v109, v102
	v_add_f32_e32 v102, v110, v102
	v_add_f32_e32 v114, v111, v102
	v_cvt_pk_bf16_f32 v126, v106, v107
	v_cvt_pk_bf16_f32 v127, v108, v109
	ds_read_b64_tr_b16 v[102:103], v186 offset:29696
	ds_read_b64_tr_b16 v[104:105], v186 offset:30208
	s_waitcnt lgkmcnt(12)
	v_mfma_f32_32x32x16_bf16 v[50:65], v[170:173], v[138:141], v[50:65]
	v_add_f32_e32 v106, v112, v114
	v_add_f32_e32 v106, v113, v106
	v_add_f32_e32 v106, v82, v106
	v_add_f32_e32 v114, v83, v106
	v_cvt_pk_bf16_f32 v128, v110, v111
	v_cvt_pk_bf16_f32 v129, v112, v113
	ds_read_b64_tr_b16 v[106:107], v186 offset:26624
	ds_read_b64_tr_b16 v[108:109], v186 offset:27136
	s_waitcnt lgkmcnt(13)
	v_mfma_f32_32x32x16_bf16 v[66:81], v[166:169], v[130:133], v[66:81]
	v_add_f32_e32 v110, v84, v114
	v_add_f32_e32 v110, v85, v110
	v_add_f32_e32 v110, v86, v110
	v_add_f32_e32 v110, v87, v110
	v_cvt_pk_bf16_f32 v118, v82, v83
	v_cvt_pk_bf16_f32 v119, v84, v85
	ds_read_b64_tr_b16 v[82:83], v186 offset:30720
	ds_read_b64_tr_b16 v[84:85], v186 offset:31232
	s_waitcnt lgkmcnt(14)
	v_mfma_f32_32x32x16_bf16 v[50:65], v[162:165], v[130:133], v[50:65]
	v_add_f32_e32 v110, v88, v110
	v_add_f32_e32 v110, v89, v110
	v_add_f32_e32 v110, v90, v110
	v_add_f32_e32 v110, v91, v110
	v_cvt_pk_bf16_f32 v120, v86, v87
	v_cvt_pk_bf16_f32 v121, v88, v89
	ds_read_b64_tr_b16 v[86:87], v186 offset:27648
	ds_read_b64_tr_b16 v[88:89], v186 offset:28160
	s_waitcnt lgkmcnt(14)
	v_mfma_f32_32x32x16_bf16 v[66:81], v[158:161], v[122:125], v[66:81]
	v_add_f32_e32 v110, v92, v110
	v_add_f32_e32 v110, v93, v110
	v_add_f32_e32 v110, v94, v110
	v_add_f32_e32 v110, v95, v110
	v_cvt_pk_bf16_f32 v114, v90, v91
	v_cvt_pk_bf16_f32 v115, v92, v93
	ds_read_b64_tr_b16 v[90:91], v186 offset:31744
	ds_read_b64_tr_b16 v[92:93], v186 offset:32256
	v_mfma_f32_32x32x16_bf16 v[50:65], v[154:157], v[122:125], v[50:65]
	v_add_f32_e32 v110, v96, v110
	v_add_f32_e32 v110, v97, v110
	v_cvt_pk_bf16_f32 v116, v94, v95
	v_cvt_pk_bf16_f32 v117, v96, v97
	s_cmpk_lt_u32 s22, 0x7c
	s_cselect_b32 s4, 0, 0xffffff80
	s_cselect_b32 s5, s9, s20
	s_add_i32 s4, s4, s23
	s_lshl_b32 s4, s4, 6
	s_add_i32 s4, s4, s5
	s_addk_i32 s4, 0x180
	s_add_i32 m0, s21, s18
	v_mad_i64_i32 v[94:95], s[4:5], s4, v217, v[192:193]
	global_load_lds_dwordx4 v[94:95], off
	v_lshl_add_u64 v[94:95], v[196:197], 0, s[30:31]
	s_add_i32 s4, s25, s19
	s_mov_b32 m0, s4
	s_nop 0
	global_load_lds_dwordx4 v[94:95], off
	v_max_f32_e32 v94, v66, v67
	v_max3_f32 v95, v68, v69, v51
	v_max3_f32 v94, v94, v50, v52
	v_max3_f32 v94, v94, v53, v70
	v_max3_f32 v95, v95, v72, v73
	v_max3_f32 v94, v94, v71, v54
	v_max3_f32 v95, v95, v56, v57
	v_max3_f32 v94, v94, v55, v74
	v_max3_f32 v95, v95, v76, v77
	v_max3_f32 v94, v94, v75, v58
	v_max3_f32 v95, v95, v60, v61
	v_max3_f32 v94, v94, v59, v78
	v_max3_f32 v95, v95, v80, v81
	v_max3_f32 v94, v94, v79, v62
	v_max3_f32 v95, v95, v64, v65
	v_max3_f32 v94, v94, v63, v95
	v_mov_b32_e32 v95, v94
	s_nop 1
	v_permlane32_swap_b32_e32 v94, v95
	v_max_f32_e32 v94, v94, v95
	v_cmp_lt_f32_e32 vcc, s51, v94
	s_cmp_lg_u64 vcc, 0
	v_add_f32_e32 v224, v224, v110
	s_cselect_b64 s[4:5], -1, 0
	s_cbranch_vccnz .LBB0_718

.LBB0_722:
	v_add_u32_e32 v186, s0, v207
	ds_read_b64_tr_b16 v[178:179], v186 offset:24576
	ds_read_b64_tr_b16 v[180:181], v186 offset:25088
	s_waitcnt lgkmcnt(9)
	v_mfma_f32_32x32x16_bf16 v[98:113], v[174:177], v[142:145], v[34:49]
	v_add_f32_e32 v82, v66, v67
	v_add_f32_e32 v82, v68, v82
	v_add_f32_e32 v82, v69, v82
	v_add_f32_e32 v82, v70, v82
	v_add_f32_e32 v82, v71, v82
	v_cvt_pk_bf16_f32 v134, v66, v67
	v_cvt_pk_bf16_f32 v135, v68, v69
	ds_read_b64_tr_b16 v[174:175], v186 offset:28672
	ds_read_b64_tr_b16 v[176:177], v186 offset:29184
	v_add_f32_e32 v66, v72, v82
	s_waitcnt lgkmcnt(10)
	v_mfma_f32_32x32x16_bf16 v[82:97], v[170:173], v[142:145], v[34:49]
	v_add_f32_e32 v66, v73, v66
	v_add_f32_e32 v66, v74, v66
	v_add_f32_e32 v114, v75, v66
	v_cvt_pk_bf16_f32 v136, v70, v71
	v_cvt_pk_bf16_f32 v137, v72, v73
	ds_read_b64_tr_b16 v[66:67], v186 offset:25600
	ds_read_b64_tr_b16 v[68:69], v186 offset:26112
	s_waitcnt lgkmcnt(11)
	v_mfma_f32_32x32x16_bf16 v[98:113], v[166:169], v[138:141], v[98:113]
	v_add_f32_e32 v70, v76, v114
	v_add_f32_e32 v70, v77, v70
	v_add_f32_e32 v70, v78, v70
	v_add_f32_e32 v114, v79, v70
	v_cvt_pk_bf16_f32 v126, v74, v75
	v_cvt_pk_bf16_f32 v127, v76, v77
	ds_read_b64_tr_b16 v[70:71], v186 offset:29696
	ds_read_b64_tr_b16 v[72:73], v186 offset:30208
	s_waitcnt lgkmcnt(12)
	v_mfma_f32_32x32x16_bf16 v[82:97], v[162:165], v[138:141], v[82:97]
	v_add_f32_e32 v74, v80, v114
	v_add_f32_e32 v74, v81, v74
	v_add_f32_e32 v74, v50, v74
	v_add_f32_e32 v114, v51, v74
	v_cvt_pk_bf16_f32 v128, v78, v79
	v_cvt_pk_bf16_f32 v129, v80, v81
	ds_read_b64_tr_b16 v[74:75], v186 offset:26624
	ds_read_b64_tr_b16 v[76:77], v186 offset:27136
	s_waitcnt lgkmcnt(13)
	v_mfma_f32_32x32x16_bf16 v[98:113], v[158:161], v[130:133], v[98:113]
	v_add_f32_e32 v78, v52, v114
	v_add_f32_e32 v78, v53, v78
	v_add_f32_e32 v78, v54, v78
	v_add_f32_e32 v78, v55, v78
	v_cvt_pk_bf16_f32 v118, v50, v51
	v_cvt_pk_bf16_f32 v119, v52, v53
	ds_read_b64_tr_b16 v[50:51], v186 offset:30720
	ds_read_b64_tr_b16 v[52:53], v186 offset:31232
	s_waitcnt lgkmcnt(14)
	v_mfma_f32_32x32x16_bf16 v[82:97], v[154:157], v[130:133], v[82:97]
	v_add_f32_e32 v78, v56, v78
	v_add_f32_e32 v78, v57, v78
	v_add_f32_e32 v78, v58, v78
	v_add_f32_e32 v78, v59, v78
	v_cvt_pk_bf16_f32 v120, v54, v55
	v_cvt_pk_bf16_f32 v121, v56, v57
	ds_read_b64_tr_b16 v[54:55], v186 offset:27648
	ds_read_b64_tr_b16 v[56:57], v186 offset:28160
	s_waitcnt lgkmcnt(14)
	v_mfma_f32_32x32x16_bf16 v[98:113], v[150:153], v[122:125], v[98:113]
	v_add_f32_e32 v78, v60, v78
	v_add_f32_e32 v78, v61, v78
	v_add_f32_e32 v78, v62, v78
	v_add_f32_e32 v78, v63, v78
	v_cvt_pk_bf16_f32 v114, v58, v59
	v_cvt_pk_bf16_f32 v115, v60, v61
	ds_read_b64_tr_b16 v[58:59], v186 offset:31744
	ds_read_b64_tr_b16 v[60:61], v186 offset:32256
	v_mfma_f32_32x32x16_bf16 v[82:97], v[146:149], v[122:125], v[82:97]
	v_add_f32_e32 v78, v64, v78
	v_add_f32_e32 v78, v65, v78
	v_cvt_pk_bf16_f32 v116, v62, v63
	v_cvt_pk_bf16_f32 v117, v64, v65
	s_cmpk_gt_u32 s21, 0x80
	s_cselect_b64 s[0:1], -1, 0
	s_and_b64 vcc, exec, s[0:1]
	s_cbranch_vccnz .LBB0_724
	s_sub_i32 s4, s20, 64
	s_add_i32 m0, s23, s18
	v_mad_i64_i32 v[62:63], s[4:5], s4, v217, v[192:193]
	global_load_lds_dwordx4 v[62:63], off
.LBB0_724:
	v_max_f32_e32 v62, v98, v99
	v_max3_f32 v63, v100, v101, v83
	v_max3_f32 v62, v62, v82, v84
	v_max3_f32 v62, v62, v85, v102
	v_max3_f32 v63, v63, v104, v105
	v_max3_f32 v62, v62, v103, v86
	v_max3_f32 v63, v63, v88, v89
	v_max3_f32 v62, v62, v87, v106
	v_max3_f32 v63, v63, v108, v109
	v_max3_f32 v62, v62, v107, v90
	v_max3_f32 v63, v63, v92, v93
	v_max3_f32 v62, v62, v91, v110
	v_max3_f32 v63, v63, v112, v113
	v_max3_f32 v62, v62, v111, v94
	v_max3_f32 v63, v63, v96, v97
	v_max3_f32 v62, v62, v95, v63
	v_mov_b32_e32 v63, v62
	s_add_i32 m0, s22, s19
	s_nop 0
	v_permlane32_swap_b32_e32 v62, v63
	global_load_lds_dwordx4 v[194:195], off
	v_max_f32_e32 v62, v62, v63
	v_cmp_lt_f32_e32 vcc, s51, v62
	s_cmp_lg_u64 vcc, 0
	v_add_f32_e32 v196, v224, v78
	s_cselect_b64 s[4:5], -1, 0
	s_cbranch_vccnz .LBB0_750
